# cand2 + K-loop headers aligned to 64 bytes
# speedup vs baseline: 1.0009x; 1.0009x over previous
; template <class Epi, class Sched, bool ALIGN_EPI = false, bool SP2 = false>
; __device__ __forceinline__ void gemm_phase(PG8_LAS unsigned char* lds, const Gemm g, const Sched& S, const Epi& E) {
;     ...
;         const bool has_next = S.next(ui + 1, nxt);
;         const char* nA = has_next ? (const char*)g.A + (size_t)nxt.pm * tstep : cA; const char* nB = has_next ? (const char*)g.Bt + (size_t)nxt.pn * tstep : cB;
;     ...
; #pragma unroll
;         for (int a = 0; a < 2; ++a)
; #pragma unroll
;             for (int b = 0; b < 2; ++b)
; #pragma unroll
;                 for (int m = 0; m < 4; ++m)
; #pragma unroll
;                     for (int n = 0; n < 2; ++n) acc[a][b][m][n] = (f32x4){0.f, 0.f, 0.f, 0.f};
;         cur = nxt; cA = nA; cB = nB; ++ui;
.LBB0_231:
	s_ashr_i32 s49, s48, 31
	s_lshl_b64 s[6:7], s[48:49], 20
	s_add_u32 s50, s96, s6
	s_addc_u32 s51, s97, s7
	s_and_b64 s[6:7], s[36:37], exec
	s_cselect_b32 s24, s51, s1
	s_cselect_b32 s25, s50, s0
	s_ashr_i32 s47, s46, 31
	s_lshl_b64 s[6:7], s[46:47], 20
	v_readlane_b32 s8, v241, 44
	s_add_u32 s52, s8, s6
	v_readlane_b32 s6, v241, 45
	s_addc_u32 s53, s6, s7
	s_and_b64 s[6:7], s[36:37], exec
	s_cselect_b32 s26, s53, s3
	s_cselect_b32 s27, s52, s2
	s_add_u32 s28, s2, 0x100
	v_mov_b32_e32 v2, 0
	s_addc_u32 s29, s3, 0
	s_mov_b32 s30, -2
	v_mov_b32_e32 v3, v2
	v_mov_b32_e32 v4, v2
	v_mov_b32_e32 v5, v2
	v_mov_b32_e32 v6, v2
	v_mov_b32_e32 v7, v2
	v_mov_b32_e32 v8, v2
	v_mov_b32_e32 v9, v2
	v_mov_b32_e32 v10, v2
	s_waitcnt lgkmcnt(0)
	v_mov_b32_e32 v11, v2
	v_mov_b32_e32 v12, v2
	v_mov_b32_e32 v13, v2
	v_mov_b32_e32 v14, v2
	v_mov_b32_e32 v15, v2
	v_mov_b32_e32 v16, v2
	v_mov_b32_e32 v17, v2
	v_mov_b32_e32 v18, v2
	v_mov_b32_e32 v19, v2
	v_mov_b32_e32 v20, v2
	v_mov_b32_e32 v21, v2
	v_mov_b32_e32 v22, v2
	v_mov_b32_e32 v23, v2
	v_mov_b32_e32 v24, v2
	v_mov_b32_e32 v25, v2
	v_mov_b32_e32 v26, v2
	v_mov_b32_e32 v27, v2
	v_mov_b32_e32 v28, v2
	v_mov_b32_e32 v29, v2
	v_mov_b32_e32 v30, v2
	v_mov_b32_e32 v31, v2
	v_mov_b32_e32 v32, v2
	v_mov_b32_e32 v33, v2
	v_mov_b32_e32 v82, v2
	v_mov_b32_e32 v83, v2
	v_mov_b32_e32 v84, v2
	v_mov_b32_e32 v85, v2
	v_mov_b32_e32 v86, v2
	v_mov_b32_e32 v87, v2
	v_mov_b32_e32 v88, v2
	v_mov_b32_e32 v89, v2
	v_mov_b32_e32 v90, v2
	v_mov_b32_e32 v91, v2
	v_mov_b32_e32 v92, v2
	v_mov_b32_e32 v93, v2
	v_mov_b32_e32 v94, v2
	v_mov_b32_e32 v95, v2
	v_mov_b32_e32 v96, v2
	v_mov_b32_e32 v97, v2
	v_mov_b32_e32 v98, v2
	v_mov_b32_e32 v99, v2
	v_mov_b32_e32 v100, v2
	v_mov_b32_e32 v101, v2
	v_mov_b32_e32 v102, v2
	v_mov_b32_e32 v103, v2
	v_mov_b32_e32 v104, v2
	v_mov_b32_e32 v105, v2
	v_mov_b32_e32 v106, v2
	v_mov_b32_e32 v107, v2
	v_mov_b32_e32 v108, v2
	v_mov_b32_e32 v109, v2
	v_mov_b32_e32 v110, v2
	v_mov_b32_e32 v111, v2
	v_mov_b32_e32 v112, v2
	v_mov_b32_e32 v113, v2
	v_mov_b32_e32 v34, v2
	v_mov_b32_e32 v35, v2
	v_mov_b32_e32 v36, v2
	v_mov_b32_e32 v37, v2
	v_mov_b32_e32 v38, v2
	v_mov_b32_e32 v39, v2
	v_mov_b32_e32 v40, v2
	v_mov_b32_e32 v41, v2
	v_mov_b32_e32 v42, v2
	v_mov_b32_e32 v43, v2
	v_mov_b32_e32 v44, v2
	v_mov_b32_e32 v45, v2
	v_mov_b32_e32 v46, v2
	v_mov_b32_e32 v47, v2
	v_mov_b32_e32 v48, v2
	v_mov_b32_e32 v49, v2
	v_mov_b32_e32 v50, v2
	v_mov_b32_e32 v51, v2
	v_mov_b32_e32 v52, v2
	v_mov_b32_e32 v53, v2
	v_mov_b32_e32 v54, v2
	v_mov_b32_e32 v55, v2
	v_mov_b32_e32 v56, v2
	v_mov_b32_e32 v57, v2
	v_mov_b32_e32 v58, v2
	v_mov_b32_e32 v59, v2
	v_mov_b32_e32 v60, v2
	v_mov_b32_e32 v61, v2
	v_mov_b32_e32 v62, v2
	v_mov_b32_e32 v63, v2
	v_mov_b32_e32 v64, v2
	v_mov_b32_e32 v65, v2
	v_mov_b32_e32 v114, v2
	v_mov_b32_e32 v115, v2
	v_mov_b32_e32 v116, v2
	v_mov_b32_e32 v117, v2
	v_mov_b32_e32 v118, v2
	v_mov_b32_e32 v119, v2
	v_mov_b32_e32 v120, v2
	v_mov_b32_e32 v121, v2
	v_mov_b32_e32 v122, v2
	v_mov_b32_e32 v123, v2
	v_mov_b32_e32 v124, v2
	v_mov_b32_e32 v125, v2
	v_mov_b32_e32 v126, v2
	v_mov_b32_e32 v127, v2
	v_mov_b32_e32 v128, v2
	v_mov_b32_e32 v129, v2
	v_mov_b32_e32 v130, v2
	v_mov_b32_e32 v131, v2
	v_mov_b32_e32 v132, v2
	v_mov_b32_e32 v133, v2
	v_mov_b32_e32 v134, v2
	v_mov_b32_e32 v135, v2
	v_mov_b32_e32 v136, v2
	v_mov_b32_e32 v137, v2
	v_mov_b32_e32 v138, v2
	v_mov_b32_e32 v139, v2
	v_mov_b32_e32 v140, v2
	v_mov_b32_e32 v141, v2
	v_mov_b32_e32 v142, v2
	v_mov_b32_e32 v143, v2
	v_mov_b32_e32 v144, v2
	v_mov_b32_e32 v145, v2
	v_add_u32_e32 v244, 0x10000, v221
	.p2align	6

; template <class Epi, class Sched, bool ALIGN_EPI = false, bool SP2 = false>
; __device__ __forceinline__ void gemm_phase(PG8_LAS unsigned char* lds, const Gemm g, const Sched& S, const Epi& E) {
;     ...
;         const bool has_next = S.next(ui + 1, nxt);
;         const char* nA = has_next ? (const char*)g.A + (size_t)nxt.pm * tstep : cA; const char* nB = has_next ? (const char*)g.Bt + (size_t)nxt.pn * tstep : cB;
;     ...
; #pragma unroll
;         for (int a = 0; a < 2; ++a)
; #pragma unroll
;             for (int b = 0; b < 2; ++b)
; #pragma unroll
;                 for (int m = 0; m < 4; ++m)
; #pragma unroll
;                     for (int n = 0; n < 2; ++n) acc[a][b][m][n] = (f32x4){0.f, 0.f, 0.f, 0.f};
;         cur = nxt; cA = nA; cB = nB; ++ui;
.LBB0_554:
	s_ashr_i32 s51, s50, 31
	v_cmp_lt_i64_e32 vcc, s[8:9], v[172:173]
	s_lshl_b64 s[8:9], s[50:51], 20
	v_readlane_b32 s10, v242, 30
	s_add_u32 s52, s10, s8
	v_readlane_b32 s8, v242, 31
	s_addc_u32 s53, s8, s9
	s_and_b64 s[8:9], vcc, exec
	s_cselect_b32 s34, s53, s5
	s_cselect_b32 s35, s52, s4
	s_ashr_i32 s49, s48, 31
	s_lshl_b64 s[8:9], s[48:49], 20
	s_add_u32 s54, s15, s8
	s_addc_u32 s55, s16, s9
	s_and_b64 s[8:9], vcc, exec
	s_cselect_b32 s38, s55, s7
	s_cselect_b32 s39, s54, s6
	s_add_u32 s40, s6, 0x100
	v_mov_b32_e32 v2, 0
	s_addc_u32 s49, s7, 0
	s_mov_b32 s51, -2
	s_waitcnt lgkmcnt(0)
	v_mov_b32_e32 v3, v2
	v_mov_b32_e32 v4, v2
	v_mov_b32_e32 v5, v2
	v_mov_b32_e32 v6, v2
	v_mov_b32_e32 v7, v2
	v_mov_b32_e32 v8, v2
	v_mov_b32_e32 v9, v2
	v_mov_b32_e32 v10, v2
	s_waitcnt lgkmcnt(0)
	v_mov_b32_e32 v11, v2
	v_mov_b32_e32 v12, v2
	v_mov_b32_e32 v13, v2
	v_mov_b32_e32 v14, v2
	v_mov_b32_e32 v15, v2
	v_mov_b32_e32 v16, v2
	v_mov_b32_e32 v17, v2
	v_mov_b32_e32 v18, v2
	v_mov_b32_e32 v19, v2
	v_mov_b32_e32 v20, v2
	v_mov_b32_e32 v21, v2
	v_mov_b32_e32 v22, v2
	v_mov_b32_e32 v23, v2
	v_mov_b32_e32 v24, v2
	v_mov_b32_e32 v25, v2
	v_mov_b32_e32 v34, v2
	v_mov_b32_e32 v35, v2
	v_mov_b32_e32 v36, v2
	v_mov_b32_e32 v37, v2
	v_mov_b32_e32 v38, v2
	v_mov_b32_e32 v39, v2
	v_mov_b32_e32 v40, v2
	v_mov_b32_e32 v41, v2
	v_mov_b32_e32 v74, v2
	v_mov_b32_e32 v75, v2
	v_mov_b32_e32 v76, v2
	v_mov_b32_e32 v77, v2
	v_mov_b32_e32 v78, v2
	v_mov_b32_e32 v79, v2
	v_mov_b32_e32 v80, v2
	v_mov_b32_e32 v81, v2
	v_mov_b32_e32 v82, v2
	v_mov_b32_e32 v83, v2
	v_mov_b32_e32 v84, v2
	v_mov_b32_e32 v85, v2
	v_mov_b32_e32 v86, v2
	v_mov_b32_e32 v87, v2
	v_mov_b32_e32 v88, v2
	v_mov_b32_e32 v89, v2
	v_mov_b32_e32 v90, v2
	v_mov_b32_e32 v91, v2
	v_mov_b32_e32 v92, v2
	v_mov_b32_e32 v93, v2
	v_mov_b32_e32 v94, v2
	v_mov_b32_e32 v95, v2
	v_mov_b32_e32 v96, v2
	v_mov_b32_e32 v97, v2
	v_mov_b32_e32 v106, v2
	v_mov_b32_e32 v107, v2
	v_mov_b32_e32 v108, v2
	v_mov_b32_e32 v109, v2
	v_mov_b32_e32 v110, v2
	v_mov_b32_e32 v111, v2
	v_mov_b32_e32 v112, v2
	v_mov_b32_e32 v113, v2
	v_mov_b32_e32 v42, v2
	v_mov_b32_e32 v43, v2
	v_mov_b32_e32 v44, v2
	v_mov_b32_e32 v45, v2
	v_mov_b32_e32 v46, v2
	v_mov_b32_e32 v47, v2
	v_mov_b32_e32 v48, v2
	v_mov_b32_e32 v49, v2
	v_mov_b32_e32 v50, v2
	v_mov_b32_e32 v51, v2
	v_mov_b32_e32 v52, v2
	v_mov_b32_e32 v53, v2
	v_mov_b32_e32 v54, v2
	v_mov_b32_e32 v55, v2
	v_mov_b32_e32 v56, v2
	v_mov_b32_e32 v57, v2
	v_mov_b32_e32 v58, v2
	v_mov_b32_e32 v59, v2
	v_mov_b32_e32 v60, v2
	v_mov_b32_e32 v61, v2
	v_mov_b32_e32 v62, v2
	v_mov_b32_e32 v63, v2
	v_mov_b32_e32 v64, v2
	v_mov_b32_e32 v65, v2
	v_mov_b32_e32 v66, v2
	v_mov_b32_e32 v67, v2
	v_mov_b32_e32 v68, v2
	v_mov_b32_e32 v69, v2
	v_mov_b32_e32 v70, v2
	v_mov_b32_e32 v71, v2
	v_mov_b32_e32 v72, v2
	v_mov_b32_e32 v73, v2
	v_mov_b32_e32 v114, v2
	v_mov_b32_e32 v115, v2
	v_mov_b32_e32 v116, v2
	v_mov_b32_e32 v117, v2
	v_mov_b32_e32 v118, v2
	v_mov_b32_e32 v119, v2
	v_mov_b32_e32 v120, v2
	v_mov_b32_e32 v121, v2
	v_mov_b32_e32 v122, v2
	v_mov_b32_e32 v123, v2
	v_mov_b32_e32 v124, v2
	v_mov_b32_e32 v125, v2
	v_mov_b32_e32 v126, v2
	v_mov_b32_e32 v127, v2
	v_mov_b32_e32 v128, v2
	v_mov_b32_e32 v129, v2
	v_mov_b32_e32 v130, v2
	v_mov_b32_e32 v131, v2
	v_mov_b32_e32 v132, v2
	v_mov_b32_e32 v133, v2
	v_mov_b32_e32 v134, v2
	v_mov_b32_e32 v135, v2
	v_mov_b32_e32 v136, v2
	v_mov_b32_e32 v137, v2
	v_mov_b32_e32 v138, v2
	v_mov_b32_e32 v139, v2
	v_mov_b32_e32 v140, v2
	v_mov_b32_e32 v141, v2
	v_mov_b32_e32 v142, v2
	v_mov_b32_e32 v143, v2
	v_mov_b32_e32 v144, v2
	v_mov_b32_e32 v145, v2
	v_add_u32_e32 v244, 0x10000, v208
	.p2align	6

; template <class Epi, class Sched, bool ALIGN_EPI = false, bool SP2 = false>
; __device__ __forceinline__ void gemm_phase(PG8_LAS unsigned char* lds, const Gemm g, const Sched& S, const Epi& E) {
;     ...
;         const bool has_next = S.next(ui + 1, nxt);
;         const char* nA = has_next ? (const char*)g.A + (size_t)nxt.pm * tstep : cA; const char* nB = has_next ? (const char*)g.Bt + (size_t)nxt.pn * tstep : cB;
;     ...
; #pragma unroll
;         for (int a = 0; a < 2; ++a)
; #pragma unroll
;             for (int b = 0; b < 2; ++b)
; #pragma unroll
;                 for (int m = 0; m < 4; ++m)
; #pragma unroll
;                     for (int n = 0; n < 2; ++n) acc[a][b][m][n] = (f32x4){0.f, 0.f, 0.f, 0.f};
;         cur = nxt; cA = nA; cB = nB; ++ui;
.LBB0_633:
	s_ashr_i32 s7, s6, 31
	s_lshl_b64 s[8:9], s[6:7], 20
	s_add_u32 s8, s96, s8
	s_addc_u32 s9, s97, s9
	s_and_b64 s[10:11], s[12:13], exec
	s_cselect_b32 s7, s9, s15
	s_cselect_b32 s49, s8, s14
	s_ashr_i32 s5, s4, 31
	s_lshl_b64 s[10:11], s[4:5], 20
	s_add_u32 s10, s24, s10
	s_addc_u32 s11, s25, s11
	s_and_b64 s[18:19], s[12:13], exec
	s_cselect_b32 s5, s11, s17
	s_cselect_b32 s50, s10, s16
	s_add_u32 s51, s16, 0x100
	v_mov_b32_e32 v2, 0
	s_addc_u32 s52, s17, 0
	s_mov_b32 s53, -2
	v_mov_b32_e32 v3, v2
	v_mov_b32_e32 v4, v2
	v_mov_b32_e32 v5, v2
	v_mov_b32_e32 v6, v2
	v_mov_b32_e32 v7, v2
	v_mov_b32_e32 v8, v2
	v_mov_b32_e32 v9, v2
	v_mov_b32_e32 v18, v2
	v_mov_b32_e32 v19, v2
	v_mov_b32_e32 v20, v2
	v_mov_b32_e32 v21, v2
	v_mov_b32_e32 v22, v2
	v_mov_b32_e32 v23, v2
	v_mov_b32_e32 v24, v2
	v_mov_b32_e32 v25, v2
	v_mov_b32_e32 v34, v2
	v_mov_b32_e32 v35, v2
	v_mov_b32_e32 v36, v2
	v_mov_b32_e32 v37, v2
	v_mov_b32_e32 v38, v2
	v_mov_b32_e32 v39, v2
	v_mov_b32_e32 v40, v2
	v_mov_b32_e32 v41, v2
	v_mov_b32_e32 v50, v2
	v_mov_b32_e32 v51, v2
	v_mov_b32_e32 v52, v2
	v_mov_b32_e32 v53, v2
	v_mov_b32_e32 v54, v2
	v_mov_b32_e32 v55, v2
	v_mov_b32_e32 v56, v2
	v_mov_b32_e32 v57, v2
	v_mov_b32_e32 v10, v2
	v_mov_b32_e32 v11, v2
	v_mov_b32_e32 v12, v2
	v_mov_b32_e32 v13, v2
	v_mov_b32_e32 v14, v2
	v_mov_b32_e32 v15, v2
	v_mov_b32_e32 v16, v2
	v_mov_b32_e32 v17, v2
	v_mov_b32_e32 v26, v2
	v_mov_b32_e32 v27, v2
	v_mov_b32_e32 v28, v2
	v_mov_b32_e32 v29, v2
	v_mov_b32_e32 v30, v2
	v_mov_b32_e32 v31, v2
	v_mov_b32_e32 v32, v2
	v_mov_b32_e32 v33, v2
	v_mov_b32_e32 v42, v2
	v_mov_b32_e32 v43, v2
	v_mov_b32_e32 v44, v2
	v_mov_b32_e32 v45, v2
	v_mov_b32_e32 v46, v2
	v_mov_b32_e32 v47, v2
	v_mov_b32_e32 v48, v2
	v_mov_b32_e32 v49, v2
	v_mov_b32_e32 v58, v2
	v_mov_b32_e32 v59, v2
	v_mov_b32_e32 v60, v2
	v_mov_b32_e32 v61, v2
	v_mov_b32_e32 v62, v2
	v_mov_b32_e32 v63, v2
	v_mov_b32_e32 v64, v2
	v_mov_b32_e32 v65, v2
	v_mov_b32_e32 v66, v2
	v_mov_b32_e32 v67, v2
	v_mov_b32_e32 v68, v2
	v_mov_b32_e32 v69, v2
	v_mov_b32_e32 v70, v2
	v_mov_b32_e32 v71, v2
	v_mov_b32_e32 v72, v2
	v_mov_b32_e32 v73, v2
	v_mov_b32_e32 v98, v2
	v_mov_b32_e32 v99, v2
	v_mov_b32_e32 v100, v2
	v_mov_b32_e32 v101, v2
	v_mov_b32_e32 v102, v2
	v_mov_b32_e32 v103, v2
	v_mov_b32_e32 v104, v2
	v_mov_b32_e32 v105, v2
	v_mov_b32_e32 v114, v2
	v_mov_b32_e32 v115, v2
	v_mov_b32_e32 v116, v2
	v_mov_b32_e32 v117, v2
	v_mov_b32_e32 v118, v2
	v_mov_b32_e32 v119, v2
	v_mov_b32_e32 v120, v2
	v_mov_b32_e32 v121, v2
	v_mov_b32_e32 v130, v2
	v_mov_b32_e32 v131, v2
	v_mov_b32_e32 v132, v2
	v_mov_b32_e32 v133, v2
	v_mov_b32_e32 v134, v2
	v_mov_b32_e32 v135, v2
	v_mov_b32_e32 v136, v2
	v_mov_b32_e32 v137, v2
	v_mov_b32_e32 v74, v2
	v_mov_b32_e32 v75, v2
	v_mov_b32_e32 v76, v2
	v_mov_b32_e32 v77, v2
	v_mov_b32_e32 v78, v2
	v_mov_b32_e32 v79, v2
	v_mov_b32_e32 v80, v2
	v_mov_b32_e32 v81, v2
	v_mov_b32_e32 v106, v2
	v_mov_b32_e32 v107, v2
	v_mov_b32_e32 v108, v2
	v_mov_b32_e32 v109, v2
	v_mov_b32_e32 v110, v2
	v_mov_b32_e32 v111, v2
	v_mov_b32_e32 v112, v2
	v_mov_b32_e32 v113, v2
	v_mov_b32_e32 v122, v2
	v_mov_b32_e32 v123, v2
	v_mov_b32_e32 v124, v2
	v_mov_b32_e32 v125, v2
	v_mov_b32_e32 v126, v2
	v_mov_b32_e32 v127, v2
	v_mov_b32_e32 v128, v2
	v_mov_b32_e32 v129, v2
	v_mov_b32_e32 v138, v2
	v_mov_b32_e32 v139, v2
	v_mov_b32_e32 v140, v2
	v_mov_b32_e32 v141, v2
	v_mov_b32_e32 v142, v2
	v_mov_b32_e32 v143, v2
	v_mov_b32_e32 v144, v2
	v_mov_b32_e32 v145, v2
	v_add_u32_e32 v244, 0x10000, v186
	.p2align	6

; template <class Epi, class Sched, bool ALIGN_EPI = false, bool SP2 = false>
; __device__ __forceinline__ void gemm_phase(PG8_LAS unsigned char* lds, const Gemm g, const Sched& S, const Epi& E) {
;     ...
;         for (int a = 0; a < 2; ++a)
; #pragma unroll
;             for (int b = 0; b < 2; ++b)
; #pragma unroll
;                 for (int m = 0; m < 4; ++m)
; #pragma unroll
;                     for (int n = 0; n < 2; ++n) acc[a][b][m][n] = (f32x4){0.f, 0.f, 0.f, 0.f};
;         cur = nxt; cA = nA; cB = nB; ++ui;
.LBB0_706:
	s_add_u32 s31, s6, 0x100
	v_mov_b32_e32 v2, 0
	s_addc_u32 s34, s7, 0
	s_mov_b32 s35, -2
	s_waitcnt lgkmcnt(0)
	v_mov_b32_e32 v3, v2
	v_mov_b32_e32 v4, v2
	v_mov_b32_e32 v5, v2
	v_mov_b32_e32 v6, v2
	v_mov_b32_e32 v7, v2
	v_mov_b32_e32 v8, v2
	v_mov_b32_e32 v9, v2
	v_mov_b32_e32 v10, v2
	v_mov_b32_e32 v11, v2
	v_mov_b32_e32 v12, v2
	v_mov_b32_e32 v13, v2
	v_mov_b32_e32 v14, v2
	v_mov_b32_e32 v15, v2
	v_mov_b32_e32 v16, v2
	v_mov_b32_e32 v17, v2
	v_mov_b32_e32 v18, v2
	v_mov_b32_e32 v19, v2
	v_mov_b32_e32 v20, v2
	v_mov_b32_e32 v21, v2
	v_mov_b32_e32 v22, v2
	v_mov_b32_e32 v23, v2
	v_mov_b32_e32 v24, v2
	v_mov_b32_e32 v25, v2
	v_mov_b32_e32 v26, v2
	v_mov_b32_e32 v27, v2
	v_mov_b32_e32 v28, v2
	v_mov_b32_e32 v29, v2
	v_mov_b32_e32 v30, v2
	v_mov_b32_e32 v31, v2
	v_mov_b32_e32 v32, v2
	v_mov_b32_e32 v33, v2
	v_mov_b32_e32 v74, v2
	v_mov_b32_e32 v75, v2
	v_mov_b32_e32 v76, v2
	v_mov_b32_e32 v77, v2
	v_mov_b32_e32 v78, v2
	v_mov_b32_e32 v79, v2
	v_mov_b32_e32 v80, v2
	v_mov_b32_e32 v81, v2
	v_mov_b32_e32 v82, v2
	v_mov_b32_e32 v83, v2
	v_mov_b32_e32 v84, v2
	v_mov_b32_e32 v85, v2
	v_mov_b32_e32 v86, v2
	v_mov_b32_e32 v87, v2
	v_mov_b32_e32 v88, v2
	v_mov_b32_e32 v89, v2
	v_mov_b32_e32 v90, v2
	v_mov_b32_e32 v91, v2
	v_mov_b32_e32 v92, v2
	v_mov_b32_e32 v93, v2
	v_mov_b32_e32 v94, v2
	v_mov_b32_e32 v95, v2
	v_mov_b32_e32 v96, v2
	v_mov_b32_e32 v97, v2
	v_mov_b32_e32 v106, v2
	v_mov_b32_e32 v107, v2
	v_mov_b32_e32 v108, v2
	v_mov_b32_e32 v109, v2
	v_mov_b32_e32 v110, v2
	v_mov_b32_e32 v111, v2
	v_mov_b32_e32 v112, v2
	v_mov_b32_e32 v113, v2
	v_mov_b32_e32 v42, v2
	v_mov_b32_e32 v43, v2
	v_mov_b32_e32 v44, v2
	v_mov_b32_e32 v45, v2
	v_mov_b32_e32 v46, v2
	v_mov_b32_e32 v47, v2
	v_mov_b32_e32 v48, v2
	v_mov_b32_e32 v49, v2
	v_mov_b32_e32 v50, v2
	v_mov_b32_e32 v51, v2
	v_mov_b32_e32 v52, v2
	v_mov_b32_e32 v53, v2
	v_mov_b32_e32 v54, v2
	v_mov_b32_e32 v55, v2
	v_mov_b32_e32 v56, v2
	v_mov_b32_e32 v57, v2
	v_mov_b32_e32 v58, v2
	v_mov_b32_e32 v59, v2
	v_mov_b32_e32 v60, v2
	v_mov_b32_e32 v61, v2
	v_mov_b32_e32 v62, v2
	v_mov_b32_e32 v63, v2
	v_mov_b32_e32 v64, v2
	v_mov_b32_e32 v65, v2
	v_mov_b32_e32 v66, v2
	v_mov_b32_e32 v67, v2
	v_mov_b32_e32 v68, v2
	v_mov_b32_e32 v69, v2
	v_mov_b32_e32 v70, v2
	v_mov_b32_e32 v71, v2
	v_mov_b32_e32 v72, v2
	v_mov_b32_e32 v73, v2
	v_mov_b32_e32 v114, v2
	v_mov_b32_e32 v115, v2
	v_mov_b32_e32 v116, v2
	v_mov_b32_e32 v117, v2
	v_mov_b32_e32 v118, v2
	v_mov_b32_e32 v119, v2
	v_mov_b32_e32 v120, v2
	v_mov_b32_e32 v121, v2
	v_mov_b32_e32 v122, v2
	v_mov_b32_e32 v123, v2
	v_mov_b32_e32 v124, v2
	v_mov_b32_e32 v125, v2
	v_mov_b32_e32 v126, v2
	v_mov_b32_e32 v127, v2
	v_mov_b32_e32 v128, v2
	v_mov_b32_e32 v129, v2
	v_mov_b32_e32 v130, v2
	v_mov_b32_e32 v131, v2
	v_mov_b32_e32 v132, v2
	v_mov_b32_e32 v133, v2
	v_mov_b32_e32 v134, v2
	v_mov_b32_e32 v135, v2
	v_mov_b32_e32 v136, v2
	v_mov_b32_e32 v137, v2
	v_mov_b32_e32 v138, v2
	v_mov_b32_e32 v139, v2
	v_mov_b32_e32 v140, v2
	v_mov_b32_e32 v141, v2
	v_mov_b32_e32 v142, v2
	v_mov_b32_e32 v143, v2
	v_mov_b32_e32 v144, v2
	v_mov_b32_e32 v145, v2
	v_add_u32_e32 v244, 0x10000, v192
	.p2align	6
